# prep: fnet weight fold restructured (row-coalesced stores, broadcast loads, paired cos/sin), ktab spread over 192 WGs, w_up and in-proj conversions de-serialized; attention max via max3+permlane swap
# speedup vs baseline: 1.0258x; 1.0071x over previous
; DI u32x4 pack8(const float* v) { u32x4 w; w.x = pk2(v[0], v[1]); w.y = pk2(v[2], v[3]); w.z = pk2(v[4], v[5]); w.w = pk2(v[6], v[7]); return w; }
; DI void convT(bf16_t* out, const float* W, int K, int Nsrc, int Npad, const float* scale, int mapid, int gtid, int nthr) {
;     const int total = Npad * (K >> 3);
;     for (int idx = gtid; idx < total; idx += nthr) {
;         const int q = idx >> 3, n = q % Npad, kc = (q / Npad) * 8 + (idx & 7), src = colmap(mapid, n);
;         float v[8];
; #pragma unroll
;         for (int j = 0; j < 8; ++j) { const int k = kc * 8 + j; v[j] = src < 0 ? 0.f : W[(size_t)k * Nsrc + src] * (scale ? scale[k] : 1.0f); }
;         *(u32x4*)(out + (size_t)n * K + kc * 8) = pack8(v);
;     }
; DI void phase_prep(const Params& P, int layer, int gtid, int nthr) {
;     ...
;     convT((bf16_t*)(wb + W_IN), IN(I_WIN) + (size_t)layer * 1024 * IN_W, 1024, IN_W, INP, IN(I_GMIX) + layer * 1024, 1, gtid, nthr);
.LBB0_39:
	s_andn2_saveexec_b64 s[8:9], s[8:9]
	v_add_u32_e32 v188, 0x300, v4
	s_or_b64 exec, exec, s[8:9]
	v_and_b32_e32 v6, 56, v1
	v_lshl_or_b32 v6, v5, 6, v6
	v_cmp_lt_i32_e64 s[10:11], -1, v188
	v_lshl_add_u64 v[8:9], v[188:189], 2, s[16:17]
	v_mov_b32_e32 v5, 0
	v_ashrrev_i32_e32 v7, 31, v6
	v_cmp_ne_u32_e64 s[12:13], 1, v3
	s_and_b64 vcc, exec, s[12:13]
	s_cbranch_vccnz .Lin_slow
	v_mov_b32_e32 v11, 0
	v_mov_b32_e32 v12, 0
	v_mov_b32_e32 v13, 0
	v_mov_b32_e32 v14, 0
	v_mov_b32_e32 v15, 0
	v_mov_b32_e32 v16, 0
	v_mov_b32_e32 v17, 0
	s_and_saveexec_b64 s[8:9], s[10:11]
	s_cbranch_execz .LBB0_18
	s_movk_i32 s0, 0x4680
	s_mov_b32 s96, 0x4680
	s_mov_b32 s97, 0
	v_mad_i64_i32 v[34:35], s[28:29], v6, s0, v[8:9]
	v_lshl_add_u64 v[36:37], v[6:7], 2, s[54:55]
	global_load_dword v18, v[34:35], off
	v_lshl_add_u64 v[34:35], v[34:35], 0, s[96:97]
	global_load_dword v19, v[34:35], off
	v_lshl_add_u64 v[34:35], v[34:35], 0, s[96:97]
	global_load_dword v20, v[34:35], off
	v_lshl_add_u64 v[34:35], v[34:35], 0, s[96:97]
	global_load_dword v21, v[34:35], off
	v_lshl_add_u64 v[34:35], v[34:35], 0, s[96:97]
	global_load_dword v22, v[34:35], off
	v_lshl_add_u64 v[34:35], v[34:35], 0, s[96:97]
	global_load_dword v23, v[34:35], off
	v_lshl_add_u64 v[34:35], v[34:35], 0, s[96:97]
	global_load_dword v24, v[34:35], off
	v_lshl_add_u64 v[34:35], v[34:35], 0, s[96:97]
	global_load_dword v25, v[34:35], off
	global_load_dwordx4 v[26:29], v[36:37], off
	global_load_dwordx4 v[30:33], v[36:37], off offset:16
	s_waitcnt vmcnt(0)
	v_mul_f32_e32 v5, v18, v26
	v_mul_f32_e32 v11, v19, v27
	v_mul_f32_e32 v12, v20, v28
	v_mul_f32_e32 v13, v21, v29
	v_mul_f32_e32 v14, v22, v30
	v_mul_f32_e32 v15, v23, v31
	v_mul_f32_e32 v16, v24, v32
	v_mul_f32_e32 v17, v25, v33
	s_branch .LBB0_18
.Lin_slow:
	s_and_saveexec_b64 s[8:9], s[10:11]
	s_cbranch_execnz .LBB0_49
	s_or_b64 exec, exec, s[8:9]
	v_mov_b32_e32 v11, 0
	s_and_saveexec_b64 s[8:9], s[10:11]
	s_cbranch_execnz .LBB0_53

; DI u32x4 pack8(const float* v) { u32x4 w; w.x = pk2(v[0], v[1]); w.y = pk2(v[2], v[3]); w.z = pk2(v[4], v[5]); w.w = pk2(v[6], v[7]); return w; }
; DI void convT(bf16_t* out, const float* W, int K, int Nsrc, int Npad, const float* scale, int mapid, int gtid, int nthr) {
;     const int total = Npad * (K >> 3);
;     for (int idx = gtid; idx < total; idx += nthr) {
;         const int q = idx >> 3, n = q % Npad, kc = (q / Npad) * 8 + (idx & 7), src = colmap(mapid, n);
;         float v[8];
; #pragma unroll
;         for (int j = 0; j < 8; ++j) { const int k = kc * 8 + j; v[j] = src < 0 ? 0.f : W[(size_t)k * Nsrc + src] * (scale ? scale[k] : 1.0f); }
;         *(u32x4*)(out + (size_t)n * K + kc * 8) = pack8(v);
;     }
; DI void phase_prep(const Params& P, int layer, int gtid, int nthr) {
;     ...
;     convT((bf16_t*)(wb + W_UP), IN(I_WUP) + (size_t)layer * 1024 * 4096, 1024, 4096, 4096, IN(I_GMLP) + layer * 1024, 0, gtid, nthr);
.LBB0_246:
	s_or_b64 exec, exec, s[6:7]
	s_mov_b32 s2, 0x80000
	v_cmp_gt_i32_e32 vcc, s2, v0
	s_and_saveexec_b64 s[6:7], vcc
	s_cbranch_execz .LBB0_307
	s_load_dwordx4 s[28:31], s[50:51], 0xa8
	v_readlane_b32 s8, v254, 58
	s_add_u32 s54, s44, 0x13f0000
	v_readlane_b32 s9, v254, 59
	s_addc_u32 s55, s45, 0
	s_lshl_b64 s[8:9], s[8:9], 24
	s_waitcnt lgkmcnt(0)
	s_add_u32 s68, s30, s8
	s_addc_u32 s69, s31, s9
	s_lshl_b64 s[14:15], s[64:65], 2
	s_add_u32 s64, s28, s14
	s_addc_u32 s65, s29, s15
	v_readlane_b32 s0, v254, 10
	s_cmp_lg_u64 s[28:29], 0
	s_mov_b64 s[76:77], 0
	v_lshl_add_u32 v1, v2, 3, s0
	s_cselect_b64 s[90:91], -1, 0
	v_mov_b32_e32 v3, v1
	v_mov_b32_e32 v8, v0
	s_andn2_b64 vcc, exec, s[90:91]
	s_cbranch_vccnz .LBB0_251
	s_mov_b32 s16, 0x4000
	s_mov_b32 s17, 0
.Lup_fast:
	v_ashrrev_i32_e32 v5, 31, v8
	v_ashrrev_i32_e32 v4, 3, v8
	v_lshrrev_b32_e32 v5, 20, v5
	v_add_u32_e32 v5, v4, v5
	v_ashrrev_i32_e32 v5, 12, v5
	v_mul_i32_i24_e32 v6, 0x1000, v5
	v_sub_u32_e32 v188, v4, v6
	v_lshlrev_b32_e32 v4, 3, v8
	v_and_b32_e32 v4, 56, v4
	v_lshl_or_b32 v4, v5, 6, v4
	v_mov_b32_e32 v5, 0
	v_lshl_add_u64 v[6:7], v[188:189], 2, s[68:69]
	v_lshlrev_b64 v[26:27], 14, v[4:5]
	v_lshl_add_u64 v[26:27], v[6:7], 0, v[26:27]
	v_lshl_add_u64 v[36:37], v[4:5], 2, s[64:65]
	global_load_dword v18, v[26:27], off
	v_lshl_add_u64 v[26:27], v[26:27], 0, s[16:17]
	global_load_dword v19, v[26:27], off
	v_lshl_add_u64 v[26:27], v[26:27], 0, s[16:17]
	global_load_dword v20, v[26:27], off
	v_lshl_add_u64 v[26:27], v[26:27], 0, s[16:17]
	global_load_dword v21, v[26:27], off
	v_lshl_add_u64 v[26:27], v[26:27], 0, s[16:17]
	global_load_dword v22, v[26:27], off
	v_lshl_add_u64 v[26:27], v[26:27], 0, s[16:17]
	global_load_dword v23, v[26:27], off
	v_lshl_add_u64 v[26:27], v[26:27], 0, s[16:17]
	global_load_dword v24, v[26:27], off
	v_lshl_add_u64 v[26:27], v[26:27], 0, s[16:17]
	global_load_dword v25, v[26:27], off
	global_load_dwordx4 v[28:31], v[36:37], off
	global_load_dwordx4 v[32:35], v[36:37], off offset:16
	v_ashrrev_i32_e32 v7, 31, v188
	v_mov_b32_e32 v6, v188
	v_lshlrev_b64 v[6:7], 11, v[6:7]
	v_lshl_add_u64 v[6:7], s[54:55], 0, v[6:7]
	v_lshl_add_u64 v[4:5], v[4:5], 1, v[6:7]
	v_add_u32_e32 v8, s84, v8
	s_mov_b32 s0, 0x7ffff
	v_cmp_lt_i32_e32 vcc, s0, v8
	s_or_b64 s[76:77], vcc, s[76:77]
	s_waitcnt vmcnt(0)
	v_mul_f32_e32 v18, v18, v28
	v_mul_f32_e32 v19, v19, v29
	v_mul_f32_e32 v20, v20, v30
	v_mul_f32_e32 v21, v21, v31
	v_mul_f32_e32 v22, v22, v32
	v_mul_f32_e32 v23, v23, v33
	v_mul_f32_e32 v24, v24, v34
	v_mul_f32_e32 v25, v25, v35
	v_cvt_pk_bf16_f32 v38, v18, v19
	v_cvt_pk_bf16_f32 v39, v20, v21
	v_cvt_pk_bf16_f32 v40, v22, v23
	v_cvt_pk_bf16_f32 v41, v24, v25
	global_store_dwordx4 v[4:5], v[38:41], off
	s_andn2_b64 exec, exec, s[76:77]
	s_cbranch_execnz .Lup_fast
	s_branch .LBB0_289

; DI unsigned f2bf(float f) { return pk2(f, 0.f) & 0xffffu; }
; DI void sincos_rev(float rev, float& s, float& c) { const float f = rev - floorf(rev); s = __builtin_amdgcn_sinf(f); c = __builtin_amdgcn_cosf(f); }
; DI void phase_prep(const Params& P, int layer, int gtid, int nthr) {
;     ...
;         const float* wf = IN(I_WFNET) + (size_t)layer * 384 * 1024; bf16_t* o = (bf16_t*)(wb + W_F);
;         for (int idx = gtid; idx < 1024 * 768; idx += nthr) {
;             const int oc = idx & 1023, kp = idx >> 10, type = kp >= 384, ch = kp - type * 384, g = ch >> 6, c = ch & 63;
;             float acc = 0.f;
;             for (int m = 0; m < 64; ++m) { float s, co; sincos_rev((float)((m * c) & 63) * (1.0f / 64.0f), s, co); acc += (type ? -s : co) * wf[(size_t)(g * 64 + m) * 1024 + oc]; }
;             o[(size_t)oc * 768 + kp] = (bf16_t)f2bf(acc * 0.125f);
;         }
.LBB0_309:
	v_and_b32_e32 v4, 63, v3
	v_bfe_u32 v8, v3, 6, 10
	v_lshrrev_b32_e32 v5, 16, v3
	v_lshlrev_b32_e32 v6, 18, v5
	v_lshl_or_b32 v6, v8, 2, v6
	s_mov_b32 s64, s50
	s_mov_b32 s65, s51
	global_load_dword v40, v6, s[64:65]
	s_add_u32 s64, s64, 0x1000
	s_addc_u32 s65, s65, 0
	global_load_dword v41, v6, s[64:65]
	s_add_u32 s64, s64, 0x1000
	s_addc_u32 s65, s65, 0
	global_load_dword v42, v6, s[64:65]
	s_add_u32 s64, s64, 0x1000
	s_addc_u32 s65, s65, 0
	global_load_dword v43, v6, s[64:65]
	s_add_u32 s64, s64, 0x1000
	s_addc_u32 s65, s65, 0
	global_load_dword v44, v6, s[64:65]
	s_add_u32 s64, s64, 0x1000
	s_addc_u32 s65, s65, 0
	global_load_dword v45, v6, s[64:65]
	s_add_u32 s64, s64, 0x1000
	s_addc_u32 s65, s65, 0
	global_load_dword v46, v6, s[64:65]
	s_add_u32 s64, s64, 0x1000
	s_addc_u32 s65, s65, 0
	global_load_dword v47, v6, s[64:65]
	s_add_u32 s64, s64, 0x1000
	s_addc_u32 s65, s65, 0
	global_load_dword v48, v6, s[64:65]
	s_add_u32 s64, s64, 0x1000
	s_addc_u32 s65, s65, 0
	global_load_dword v49, v6, s[64:65]
	s_add_u32 s64, s64, 0x1000
	s_addc_u32 s65, s65, 0
	global_load_dword v50, v6, s[64:65]
	s_add_u32 s64, s64, 0x1000
	s_addc_u32 s65, s65, 0
	global_load_dword v51, v6, s[64:65]
	s_add_u32 s64, s64, 0x1000
	s_addc_u32 s65, s65, 0
	global_load_dword v52, v6, s[64:65]
	s_add_u32 s64, s64, 0x1000
	s_addc_u32 s65, s65, 0
	global_load_dword v53, v6, s[64:65]
	s_add_u32 s64, s64, 0x1000
	s_addc_u32 s65, s65, 0
	global_load_dword v54, v6, s[64:65]
	s_add_u32 s64, s64, 0x1000
	s_addc_u32 s65, s65, 0
	global_load_dword v55, v6, s[64:65]
	s_add_u32 s64, s64, 0x1000
	s_addc_u32 s65, s65, 0
	global_load_dword v56, v6, s[64:65]
	s_add_u32 s64, s64, 0x1000
	s_addc_u32 s65, s65, 0
	global_load_dword v57, v6, s[64:65]
	s_add_u32 s64, s64, 0x1000
	s_addc_u32 s65, s65, 0
	global_load_dword v58, v6, s[64:65]
	s_add_u32 s64, s64, 0x1000
	s_addc_u32 s65, s65, 0
	global_load_dword v59, v6, s[64:65]
	s_add_u32 s64, s64, 0x1000
	s_addc_u32 s65, s65, 0
	global_load_dword v60, v6, s[64:65]
	s_add_u32 s64, s64, 0x1000
	s_addc_u32 s65, s65, 0
	global_load_dword v61, v6, s[64:65]
	s_add_u32 s64, s64, 0x1000
	s_addc_u32 s65, s65, 0
	global_load_dword v62, v6, s[64:65]
	s_add_u32 s64, s64, 0x1000
	s_addc_u32 s65, s65, 0
	global_load_dword v63, v6, s[64:65]
	s_add_u32 s64, s64, 0x1000
	s_addc_u32 s65, s65, 0
	global_load_dword v64, v6, s[64:65]
	s_add_u32 s64, s64, 0x1000
	s_addc_u32 s65, s65, 0
	global_load_dword v65, v6, s[64:65]
	s_add_u32 s64, s64, 0x1000
	s_addc_u32 s65, s65, 0
	global_load_dword v66, v6, s[64:65]
	s_add_u32 s64, s64, 0x1000
	s_addc_u32 s65, s65, 0
	global_load_dword v67, v6, s[64:65]
	s_add_u32 s64, s64, 0x1000
	s_addc_u32 s65, s65, 0
	global_load_dword v68, v6, s[64:65]
	s_add_u32 s64, s64, 0x1000
	s_addc_u32 s65, s65, 0
	global_load_dword v69, v6, s[64:65]
	s_add_u32 s64, s64, 0x1000
	s_addc_u32 s65, s65, 0
	global_load_dword v70, v6, s[64:65]
	s_add_u32 s64, s64, 0x1000
	s_addc_u32 s65, s65, 0
	global_load_dword v71, v6, s[64:65]
	s_add_u32 s64, s64, 0x1000
	s_addc_u32 s65, s65, 0
	global_load_dword v72, v6, s[64:65]
	s_add_u32 s64, s64, 0x1000
	s_addc_u32 s65, s65, 0
	global_load_dword v73, v6, s[64:65]
	s_add_u32 s64, s64, 0x1000
	s_addc_u32 s65, s65, 0
	global_load_dword v74, v6, s[64:65]
	s_add_u32 s64, s64, 0x1000
	s_addc_u32 s65, s65, 0
	global_load_dword v75, v6, s[64:65]
	s_add_u32 s64, s64, 0x1000
	s_addc_u32 s65, s65, 0
	global_load_dword v76, v6, s[64:65]
	s_add_u32 s64, s64, 0x1000
	s_addc_u32 s65, s65, 0
	global_load_dword v77, v6, s[64:65]
	s_add_u32 s64, s64, 0x1000
	s_addc_u32 s65, s65, 0
	global_load_dword v78, v6, s[64:65]
	s_add_u32 s64, s64, 0x1000
	s_addc_u32 s65, s65, 0
	global_load_dword v79, v6, s[64:65]
	s_add_u32 s64, s64, 0x1000
	s_addc_u32 s65, s65, 0
	global_load_dword v80, v6, s[64:65]
	s_add_u32 s64, s64, 0x1000
	s_addc_u32 s65, s65, 0
	global_load_dword v81, v6, s[64:65]
	s_add_u32 s64, s64, 0x1000
	s_addc_u32 s65, s65, 0
	global_load_dword v82, v6, s[64:65]
	s_add_u32 s64, s64, 0x1000
	s_addc_u32 s65, s65, 0
	global_load_dword v83, v6, s[64:65]
	s_add_u32 s64, s64, 0x1000
	s_addc_u32 s65, s65, 0
	global_load_dword v84, v6, s[64:65]
	s_add_u32 s64, s64, 0x1000
	s_addc_u32 s65, s65, 0
	global_load_dword v85, v6, s[64:65]
	s_add_u32 s64, s64, 0x1000
	s_addc_u32 s65, s65, 0
	global_load_dword v86, v6, s[64:65]
	s_add_u32 s64, s64, 0x1000
	s_addc_u32 s65, s65, 0
	global_load_dword v87, v6, s[64:65]
	s_add_u32 s64, s64, 0x1000
	s_addc_u32 s65, s65, 0
	global_load_dword v88, v6, s[64:65]
	s_add_u32 s64, s64, 0x1000
	s_addc_u32 s65, s65, 0
	global_load_dword v89, v6, s[64:65]
	s_add_u32 s64, s64, 0x1000
	s_addc_u32 s65, s65, 0
	global_load_dword v90, v6, s[64:65]
	s_add_u32 s64, s64, 0x1000
	s_addc_u32 s65, s65, 0
	global_load_dword v91, v6, s[64:65]
	s_add_u32 s64, s64, 0x1000
	s_addc_u32 s65, s65, 0
	global_load_dword v92, v6, s[64:65]
	s_add_u32 s64, s64, 0x1000
	s_addc_u32 s65, s65, 0
	global_load_dword v93, v6, s[64:65]
	s_add_u32 s64, s64, 0x1000
	s_addc_u32 s65, s65, 0
	global_load_dword v94, v6, s[64:65]
	s_add_u32 s64, s64, 0x1000
	s_addc_u32 s65, s65, 0
	global_load_dword v95, v6, s[64:65]
	s_add_u32 s64, s64, 0x1000
	s_addc_u32 s65, s65, 0
	global_load_dword v96, v6, s[64:65]
	s_add_u32 s64, s64, 0x1000
	s_addc_u32 s65, s65, 0
	global_load_dword v97, v6, s[64:65]
	s_add_u32 s64, s64, 0x1000
	s_addc_u32 s65, s65, 0
	global_load_dword v98, v6, s[64:65]
	s_add_u32 s64, s64, 0x1000
	s_addc_u32 s65, s65, 0
	global_load_dword v99, v6, s[64:65]
	s_add_u32 s64, s64, 0x1000
	s_addc_u32 s65, s65, 0
	global_load_dword v100, v6, s[64:65]
	s_add_u32 s64, s64, 0x1000
	s_addc_u32 s65, s65, 0
	global_load_dword v101, v6, s[64:65]
	s_add_u32 s64, s64, 0x1000
	s_addc_u32 s65, s65, 0
	global_load_dword v102, v6, s[64:65]
	s_add_u32 s64, s64, 0x1000
	s_addc_u32 s65, s65, 0
	global_load_dword v103, v6, s[64:65]
	v_mov_b32_e32 v15, 0
	v_mov_b32_e32 v20, 0
	v_mov_b32_e32 v16, 0
	v_and_b32_e32 v17, 63, v16
	v_cvt_f32_ubyte0_e32 v17, v17
	v_mul_f32_e32 v17, 0x3c800000, v17
	v_cos_f32_e32 v18, v17
	v_sin_f32_e64 v19, -v17
	v_add_u32_e32 v16, v16, v4
	s_waitcnt vmcnt(63)
; DI unsigned f2bf(float f) { return pk2(f, 0.f) & 0xffffu; }
; DI void sincos_rev(float rev, float& s, float& c) { const float f = rev - floorf(rev); s = __builtin_amdgcn_sinf(f); c = __builtin_amdgcn_cosf(f); }
; DI void phase_prep(const Params& P, int layer, int gtid, int nthr) {
;     ...
;         const float* wf = IN(I_WFNET) + (size_t)layer * 384 * 1024; bf16_t* o = (bf16_t*)(wb + W_F);
;         for (int idx = gtid; idx < 1024 * 768; idx += nthr) {
;             const int oc = idx & 1023, kp = idx >> 10, type = kp >= 384, ch = kp - type * 384, g = ch >> 6, c = ch & 63;
;             float acc = 0.f;
;             for (int m = 0; m < 64; ++m) { float s, co; sincos_rev((float)((m * c) & 63) * (1.0f / 64.0f), s, co); acc += (type ? -s : co) * wf[(size_t)(g * 64 + m) * 1024 + oc]; }
;             o[(size_t)oc * 768 + kp] = (bf16_t)f2bf(acc * 0.125f);
;         }
	v_fmac_f32_e32 v15, v40, v18
	v_fmac_f32_e32 v20, v40, v19
	v_and_b32_e32 v17, 63, v16
	v_cvt_f32_ubyte0_e32 v17, v17
	v_mul_f32_e32 v17, 0x3c800000, v17
	v_cos_f32_e32 v18, v17
	v_sin_f32_e64 v19, -v17
	v_add_u32_e32 v16, v16, v4
	s_waitcnt vmcnt(62)
	v_fmac_f32_e32 v15, v41, v18
	v_fmac_f32_e32 v20, v41, v19
	v_and_b32_e32 v17, 63, v16
	v_cvt_f32_ubyte0_e32 v17, v17
	v_mul_f32_e32 v17, 0x3c800000, v17
	v_cos_f32_e32 v18, v17
	v_sin_f32_e64 v19, -v17
	v_add_u32_e32 v16, v16, v4
	s_waitcnt vmcnt(61)
	v_fmac_f32_e32 v15, v42, v18
	v_fmac_f32_e32 v20, v42, v19
	v_and_b32_e32 v17, 63, v16
	v_cvt_f32_ubyte0_e32 v17, v17
	v_mul_f32_e32 v17, 0x3c800000, v17
	v_cos_f32_e32 v18, v17
	v_sin_f32_e64 v19, -v17
	v_add_u32_e32 v16, v16, v4
	s_waitcnt vmcnt(60)
	v_fmac_f32_e32 v15, v43, v18
	v_fmac_f32_e32 v20, v43, v19
	v_and_b32_e32 v17, 63, v16
	v_cvt_f32_ubyte0_e32 v17, v17
	v_mul_f32_e32 v17, 0x3c800000, v17
	v_cos_f32_e32 v18, v17
	v_sin_f32_e64 v19, -v17
	v_add_u32_e32 v16, v16, v4
	s_waitcnt vmcnt(59)
	v_fmac_f32_e32 v15, v44, v18
	v_fmac_f32_e32 v20, v44, v19
	v_and_b32_e32 v17, 63, v16
	v_cvt_f32_ubyte0_e32 v17, v17
	v_mul_f32_e32 v17, 0x3c800000, v17
	v_cos_f32_e32 v18, v17
	v_sin_f32_e64 v19, -v17
	v_add_u32_e32 v16, v16, v4
	s_waitcnt vmcnt(58)
	v_fmac_f32_e32 v15, v45, v18
	v_fmac_f32_e32 v20, v45, v19
	v_and_b32_e32 v17, 63, v16
	v_cvt_f32_ubyte0_e32 v17, v17
	v_mul_f32_e32 v17, 0x3c800000, v17
	v_cos_f32_e32 v18, v17
	v_sin_f32_e64 v19, -v17
	v_add_u32_e32 v16, v16, v4
	s_waitcnt vmcnt(57)
	v_fmac_f32_e32 v15, v46, v18
	v_fmac_f32_e32 v20, v46, v19
	v_and_b32_e32 v17, 63, v16
	v_cvt_f32_ubyte0_e32 v17, v17
	v_mul_f32_e32 v17, 0x3c800000, v17
	v_cos_f32_e32 v18, v17
	v_sin_f32_e64 v19, -v17
	v_add_u32_e32 v16, v16, v4
	s_waitcnt vmcnt(56)
	v_fmac_f32_e32 v15, v47, v18
	v_fmac_f32_e32 v20, v47, v19
	v_and_b32_e32 v17, 63, v16
	v_cvt_f32_ubyte0_e32 v17, v17
	v_mul_f32_e32 v17, 0x3c800000, v17
	v_cos_f32_e32 v18, v17
	v_sin_f32_e64 v19, -v17
	v_add_u32_e32 v16, v16, v4
	s_waitcnt vmcnt(55)
	v_fmac_f32_e32 v15, v48, v18
	v_fmac_f32_e32 v20, v48, v19
	v_and_b32_e32 v17, 63, v16
	v_cvt_f32_ubyte0_e32 v17, v17
	v_mul_f32_e32 v17, 0x3c800000, v17
	v_cos_f32_e32 v18, v17
	v_sin_f32_e64 v19, -v17
	v_add_u32_e32 v16, v16, v4
	s_waitcnt vmcnt(54)
	v_fmac_f32_e32 v15, v49, v18
	v_fmac_f32_e32 v20, v49, v19
	v_and_b32_e32 v17, 63, v16
	v_cvt_f32_ubyte0_e32 v17, v17
	v_mul_f32_e32 v17, 0x3c800000, v17
	v_cos_f32_e32 v18, v17
	v_sin_f32_e64 v19, -v17
	v_add_u32_e32 v16, v16, v4
	s_waitcnt vmcnt(53)
	v_fmac_f32_e32 v15, v50, v18
	v_fmac_f32_e32 v20, v50, v19
	v_and_b32_e32 v17, 63, v16
	v_cvt_f32_ubyte0_e32 v17, v17
	v_mul_f32_e32 v17, 0x3c800000, v17
	v_cos_f32_e32 v18, v17
	v_sin_f32_e64 v19, -v17
	v_add_u32_e32 v16, v16, v4
	s_waitcnt vmcnt(52)
	v_fmac_f32_e32 v15, v51, v18
	v_fmac_f32_e32 v20, v51, v19
	v_and_b32_e32 v17, 63, v16
	v_cvt_f32_ubyte0_e32 v17, v17
	v_mul_f32_e32 v17, 0x3c800000, v17
	v_cos_f32_e32 v18, v17
	v_sin_f32_e64 v19, -v17
	v_add_u32_e32 v16, v16, v4
	s_waitcnt vmcnt(51)
	v_fmac_f32_e32 v15, v52, v18
	v_fmac_f32_e32 v20, v52, v19
	v_and_b32_e32 v17, 63, v16
	v_cvt_f32_ubyte0_e32 v17, v17
	v_mul_f32_e32 v17, 0x3c800000, v17
	v_cos_f32_e32 v18, v17
	v_sin_f32_e64 v19, -v17
	v_add_u32_e32 v16, v16, v4
	s_waitcnt vmcnt(50)
	v_fmac_f32_e32 v15, v53, v18
	v_fmac_f32_e32 v20, v53, v19
	v_and_b32_e32 v17, 63, v16
	v_cvt_f32_ubyte0_e32 v17, v17
	v_mul_f32_e32 v17, 0x3c800000, v17
	v_cos_f32_e32 v18, v17
	v_sin_f32_e64 v19, -v17
	v_add_u32_e32 v16, v16, v4
	s_waitcnt vmcnt(49)
	v_fmac_f32_e32 v15, v54, v18
	v_fmac_f32_e32 v20, v54, v19
	v_and_b32_e32 v17, 63, v16
	v_cvt_f32_ubyte0_e32 v17, v17
	v_mul_f32_e32 v17, 0x3c800000, v17
	v_cos_f32_e32 v18, v17
	v_sin_f32_e64 v19, -v17
	v_add_u32_e32 v16, v16, v4
	s_waitcnt vmcnt(48)
	v_fmac_f32_e32 v15, v55, v18
	v_fmac_f32_e32 v20, v55, v19
	v_and_b32_e32 v17, 63, v16
	v_cvt_f32_ubyte0_e32 v17, v17
	v_mul_f32_e32 v17, 0x3c800000, v17
	v_cos_f32_e32 v18, v17
	v_sin_f32_e64 v19, -v17
	v_add_u32_e32 v16, v16, v4
	s_waitcnt vmcnt(47)
	v_fmac_f32_e32 v15, v56, v18
	v_fmac_f32_e32 v20, v56, v19
	v_and_b32_e32 v17, 63, v16
	v_cvt_f32_ubyte0_e32 v17, v17
	v_mul_f32_e32 v17, 0x3c800000, v17
	v_cos_f32_e32 v18, v17
	v_sin_f32_e64 v19, -v17
	v_add_u32_e32 v16, v16, v4
	s_waitcnt vmcnt(46)
	v_fmac_f32_e32 v15, v57, v18
	v_fmac_f32_e32 v20, v57, v19
	v_and_b32_e32 v17, 63, v16
	v_cvt_f32_ubyte0_e32 v17, v17
	v_mul_f32_e32 v17, 0x3c800000, v17
	v_cos_f32_e32 v18, v17
	v_sin_f32_e64 v19, -v17
	v_add_u32_e32 v16, v16, v4
	s_waitcnt vmcnt(45)
	v_fmac_f32_e32 v15, v58, v18
	v_fmac_f32_e32 v20, v58, v19
	v_and_b32_e32 v17, 63, v16
	v_cvt_f32_ubyte0_e32 v17, v17
	v_mul_f32_e32 v17, 0x3c800000, v17
	v_cos_f32_e32 v18, v17
	v_sin_f32_e64 v19, -v17
	v_add_u32_e32 v16, v16, v4
	s_waitcnt vmcnt(44)
	v_fmac_f32_e32 v15, v59, v18
	v_fmac_f32_e32 v20, v59, v19
	v_and_b32_e32 v17, 63, v16
	v_cvt_f32_ubyte0_e32 v17, v17
	v_mul_f32_e32 v17, 0x3c800000, v17
	v_cos_f32_e32 v18, v17
	v_sin_f32_e64 v19, -v17
	v_add_u32_e32 v16, v16, v4
	s_waitcnt vmcnt(43)
	v_fmac_f32_e32 v15, v60, v18
	v_fmac_f32_e32 v20, v60, v19
	v_and_b32_e32 v17, 63, v16
	v_cvt_f32_ubyte0_e32 v17, v17
	v_mul_f32_e32 v17, 0x3c800000, v17
	v_cos_f32_e32 v18, v17
	v_sin_f32_e64 v19, -v17
	v_add_u32_e32 v16, v16, v4
	s_waitcnt vmcnt(42)
	v_fmac_f32_e32 v15, v61, v18
	v_fmac_f32_e32 v20, v61, v19
	v_and_b32_e32 v17, 63, v16
	v_cvt_f32_ubyte0_e32 v17, v17
	v_mul_f32_e32 v17, 0x3c800000, v17
	v_cos_f32_e32 v18, v17
	v_sin_f32_e64 v19, -v17
	v_add_u32_e32 v16, v16, v4
	s_waitcnt vmcnt(41)
; DI unsigned f2bf(float f) { return pk2(f, 0.f) & 0xffffu; }
; DI void sincos_rev(float rev, float& s, float& c) { const float f = rev - floorf(rev); s = __builtin_amdgcn_sinf(f); c = __builtin_amdgcn_cosf(f); }
; DI void phase_prep(const Params& P, int layer, int gtid, int nthr) {
;     ...
;         const float* wf = IN(I_WFNET) + (size_t)layer * 384 * 1024; bf16_t* o = (bf16_t*)(wb + W_F);
;         for (int idx = gtid; idx < 1024 * 768; idx += nthr) {
;             const int oc = idx & 1023, kp = idx >> 10, type = kp >= 384, ch = kp - type * 384, g = ch >> 6, c = ch & 63;
;             float acc = 0.f;
;             for (int m = 0; m < 64; ++m) { float s, co; sincos_rev((float)((m * c) & 63) * (1.0f / 64.0f), s, co); acc += (type ? -s : co) * wf[(size_t)(g * 64 + m) * 1024 + oc]; }
;             o[(size_t)oc * 768 + kp] = (bf16_t)f2bf(acc * 0.125f);
;         }
	v_fmac_f32_e32 v15, v62, v18
	v_fmac_f32_e32 v20, v62, v19
	v_and_b32_e32 v17, 63, v16
	v_cvt_f32_ubyte0_e32 v17, v17
	v_mul_f32_e32 v17, 0x3c800000, v17
	v_cos_f32_e32 v18, v17
	v_sin_f32_e64 v19, -v17
	v_add_u32_e32 v16, v16, v4
	s_waitcnt vmcnt(40)
	v_fmac_f32_e32 v15, v63, v18
	v_fmac_f32_e32 v20, v63, v19
	v_and_b32_e32 v17, 63, v16
	v_cvt_f32_ubyte0_e32 v17, v17
	v_mul_f32_e32 v17, 0x3c800000, v17
	v_cos_f32_e32 v18, v17
	v_sin_f32_e64 v19, -v17
	v_add_u32_e32 v16, v16, v4
	s_waitcnt vmcnt(39)
	v_fmac_f32_e32 v15, v64, v18
	v_fmac_f32_e32 v20, v64, v19
	v_and_b32_e32 v17, 63, v16
	v_cvt_f32_ubyte0_e32 v17, v17
	v_mul_f32_e32 v17, 0x3c800000, v17
	v_cos_f32_e32 v18, v17
	v_sin_f32_e64 v19, -v17
	v_add_u32_e32 v16, v16, v4
	s_waitcnt vmcnt(38)
	v_fmac_f32_e32 v15, v65, v18
	v_fmac_f32_e32 v20, v65, v19
	v_and_b32_e32 v17, 63, v16
	v_cvt_f32_ubyte0_e32 v17, v17
	v_mul_f32_e32 v17, 0x3c800000, v17
	v_cos_f32_e32 v18, v17
	v_sin_f32_e64 v19, -v17
	v_add_u32_e32 v16, v16, v4
	s_waitcnt vmcnt(37)
	v_fmac_f32_e32 v15, v66, v18
	v_fmac_f32_e32 v20, v66, v19
	v_and_b32_e32 v17, 63, v16
	v_cvt_f32_ubyte0_e32 v17, v17
	v_mul_f32_e32 v17, 0x3c800000, v17
	v_cos_f32_e32 v18, v17
	v_sin_f32_e64 v19, -v17
	v_add_u32_e32 v16, v16, v4
	s_waitcnt vmcnt(36)
	v_fmac_f32_e32 v15, v67, v18
	v_fmac_f32_e32 v20, v67, v19
	v_and_b32_e32 v17, 63, v16
	v_cvt_f32_ubyte0_e32 v17, v17
	v_mul_f32_e32 v17, 0x3c800000, v17
	v_cos_f32_e32 v18, v17
	v_sin_f32_e64 v19, -v17
	v_add_u32_e32 v16, v16, v4
	s_waitcnt vmcnt(35)
	v_fmac_f32_e32 v15, v68, v18
	v_fmac_f32_e32 v20, v68, v19
	v_and_b32_e32 v17, 63, v16
	v_cvt_f32_ubyte0_e32 v17, v17
	v_mul_f32_e32 v17, 0x3c800000, v17
	v_cos_f32_e32 v18, v17
	v_sin_f32_e64 v19, -v17
	v_add_u32_e32 v16, v16, v4
	s_waitcnt vmcnt(34)
	v_fmac_f32_e32 v15, v69, v18
	v_fmac_f32_e32 v20, v69, v19
	v_and_b32_e32 v17, 63, v16
	v_cvt_f32_ubyte0_e32 v17, v17
	v_mul_f32_e32 v17, 0x3c800000, v17
	v_cos_f32_e32 v18, v17
	v_sin_f32_e64 v19, -v17
	v_add_u32_e32 v16, v16, v4
	s_waitcnt vmcnt(33)
	v_fmac_f32_e32 v15, v70, v18
	v_fmac_f32_e32 v20, v70, v19
	v_and_b32_e32 v17, 63, v16
	v_cvt_f32_ubyte0_e32 v17, v17
	v_mul_f32_e32 v17, 0x3c800000, v17
	v_cos_f32_e32 v18, v17
	v_sin_f32_e64 v19, -v17
	v_add_u32_e32 v16, v16, v4
	s_waitcnt vmcnt(32)
	v_fmac_f32_e32 v15, v71, v18
	v_fmac_f32_e32 v20, v71, v19
	v_and_b32_e32 v17, 63, v16
	v_cvt_f32_ubyte0_e32 v17, v17
	v_mul_f32_e32 v17, 0x3c800000, v17
	v_cos_f32_e32 v18, v17
	v_sin_f32_e64 v19, -v17
	v_add_u32_e32 v16, v16, v4
	s_waitcnt vmcnt(31)
	v_fmac_f32_e32 v15, v72, v18
	v_fmac_f32_e32 v20, v72, v19
	v_and_b32_e32 v17, 63, v16
	v_cvt_f32_ubyte0_e32 v17, v17
	v_mul_f32_e32 v17, 0x3c800000, v17
	v_cos_f32_e32 v18, v17
	v_sin_f32_e64 v19, -v17
	v_add_u32_e32 v16, v16, v4
	s_waitcnt vmcnt(30)
	v_fmac_f32_e32 v15, v73, v18
	v_fmac_f32_e32 v20, v73, v19
	v_and_b32_e32 v17, 63, v16
	v_cvt_f32_ubyte0_e32 v17, v17
	v_mul_f32_e32 v17, 0x3c800000, v17
	v_cos_f32_e32 v18, v17
	v_sin_f32_e64 v19, -v17
	v_add_u32_e32 v16, v16, v4
	s_waitcnt vmcnt(29)
	v_fmac_f32_e32 v15, v74, v18
	v_fmac_f32_e32 v20, v74, v19
	v_and_b32_e32 v17, 63, v16
	v_cvt_f32_ubyte0_e32 v17, v17
	v_mul_f32_e32 v17, 0x3c800000, v17
	v_cos_f32_e32 v18, v17
	v_sin_f32_e64 v19, -v17
	v_add_u32_e32 v16, v16, v4
	s_waitcnt vmcnt(28)
	v_fmac_f32_e32 v15, v75, v18
	v_fmac_f32_e32 v20, v75, v19
	v_and_b32_e32 v17, 63, v16
	v_cvt_f32_ubyte0_e32 v17, v17
	v_mul_f32_e32 v17, 0x3c800000, v17
	v_cos_f32_e32 v18, v17
	v_sin_f32_e64 v19, -v17
	v_add_u32_e32 v16, v16, v4
	s_waitcnt vmcnt(27)
	v_fmac_f32_e32 v15, v76, v18
	v_fmac_f32_e32 v20, v76, v19
	v_and_b32_e32 v17, 63, v16
	v_cvt_f32_ubyte0_e32 v17, v17
	v_mul_f32_e32 v17, 0x3c800000, v17
	v_cos_f32_e32 v18, v17
	v_sin_f32_e64 v19, -v17
	v_add_u32_e32 v16, v16, v4
	s_waitcnt vmcnt(26)
	v_fmac_f32_e32 v15, v77, v18
	v_fmac_f32_e32 v20, v77, v19
	v_and_b32_e32 v17, 63, v16
	v_cvt_f32_ubyte0_e32 v17, v17
	v_mul_f32_e32 v17, 0x3c800000, v17
	v_cos_f32_e32 v18, v17
	v_sin_f32_e64 v19, -v17
	v_add_u32_e32 v16, v16, v4
	s_waitcnt vmcnt(25)
	v_fmac_f32_e32 v15, v78, v18
	v_fmac_f32_e32 v20, v78, v19
	v_and_b32_e32 v17, 63, v16
	v_cvt_f32_ubyte0_e32 v17, v17
	v_mul_f32_e32 v17, 0x3c800000, v17
	v_cos_f32_e32 v18, v17
	v_sin_f32_e64 v19, -v17
	v_add_u32_e32 v16, v16, v4
	s_waitcnt vmcnt(24)
	v_fmac_f32_e32 v15, v79, v18
	v_fmac_f32_e32 v20, v79, v19
	v_and_b32_e32 v17, 63, v16
	v_cvt_f32_ubyte0_e32 v17, v17
	v_mul_f32_e32 v17, 0x3c800000, v17
	v_cos_f32_e32 v18, v17
	v_sin_f32_e64 v19, -v17
	v_add_u32_e32 v16, v16, v4
	s_waitcnt vmcnt(23)
	v_fmac_f32_e32 v15, v80, v18
	v_fmac_f32_e32 v20, v80, v19
	v_and_b32_e32 v17, 63, v16
	v_cvt_f32_ubyte0_e32 v17, v17
	v_mul_f32_e32 v17, 0x3c800000, v17
	v_cos_f32_e32 v18, v17
	v_sin_f32_e64 v19, -v17
	v_add_u32_e32 v16, v16, v4
	s_waitcnt vmcnt(22)
	v_fmac_f32_e32 v15, v81, v18
	v_fmac_f32_e32 v20, v81, v19
	v_and_b32_e32 v17, 63, v16
	v_cvt_f32_ubyte0_e32 v17, v17
	v_mul_f32_e32 v17, 0x3c800000, v17
	v_cos_f32_e32 v18, v17
	v_sin_f32_e64 v19, -v17
	v_add_u32_e32 v16, v16, v4
	s_waitcnt vmcnt(21)
	v_fmac_f32_e32 v15, v82, v18
	v_fmac_f32_e32 v20, v82, v19
	v_and_b32_e32 v17, 63, v16
	v_cvt_f32_ubyte0_e32 v17, v17
	v_mul_f32_e32 v17, 0x3c800000, v17
	v_cos_f32_e32 v18, v17
	v_sin_f32_e64 v19, -v17
	v_add_u32_e32 v16, v16, v4
	s_waitcnt vmcnt(20)
	v_fmac_f32_e32 v15, v83, v18
	v_fmac_f32_e32 v20, v83, v19
	v_and_b32_e32 v17, 63, v16
	v_cvt_f32_ubyte0_e32 v17, v17
	v_mul_f32_e32 v17, 0x3c800000, v17
	v_cos_f32_e32 v18, v17
	v_sin_f32_e64 v19, -v17
	v_add_u32_e32 v16, v16, v4
	s_waitcnt vmcnt(19)
; DI unsigned f2bf(float f) { return pk2(f, 0.f) & 0xffffu; }
; DI void sincos_rev(float rev, float& s, float& c) { const float f = rev - floorf(rev); s = __builtin_amdgcn_sinf(f); c = __builtin_amdgcn_cosf(f); }
; DI void phase_prep(const Params& P, int layer, int gtid, int nthr) {
;     ...
;         const float* wf = IN(I_WFNET) + (size_t)layer * 384 * 1024; bf16_t* o = (bf16_t*)(wb + W_F);
;         for (int idx = gtid; idx < 1024 * 768; idx += nthr) {
;             const int oc = idx & 1023, kp = idx >> 10, type = kp >= 384, ch = kp - type * 384, g = ch >> 6, c = ch & 63;
;             float acc = 0.f;
;             for (int m = 0; m < 64; ++m) { float s, co; sincos_rev((float)((m * c) & 63) * (1.0f / 64.0f), s, co); acc += (type ? -s : co) * wf[(size_t)(g * 64 + m) * 1024 + oc]; }
;             o[(size_t)oc * 768 + kp] = (bf16_t)f2bf(acc * 0.125f);
;         }
	v_fmac_f32_e32 v15, v84, v18
	v_fmac_f32_e32 v20, v84, v19
	v_and_b32_e32 v17, 63, v16
	v_cvt_f32_ubyte0_e32 v17, v17
	v_mul_f32_e32 v17, 0x3c800000, v17
	v_cos_f32_e32 v18, v17
	v_sin_f32_e64 v19, -v17
	v_add_u32_e32 v16, v16, v4
	s_waitcnt vmcnt(18)
	v_fmac_f32_e32 v15, v85, v18
	v_fmac_f32_e32 v20, v85, v19
	v_and_b32_e32 v17, 63, v16
	v_cvt_f32_ubyte0_e32 v17, v17
	v_mul_f32_e32 v17, 0x3c800000, v17
	v_cos_f32_e32 v18, v17
	v_sin_f32_e64 v19, -v17
	v_add_u32_e32 v16, v16, v4
	s_waitcnt vmcnt(17)
	v_fmac_f32_e32 v15, v86, v18
	v_fmac_f32_e32 v20, v86, v19
	v_and_b32_e32 v17, 63, v16
	v_cvt_f32_ubyte0_e32 v17, v17
	v_mul_f32_e32 v17, 0x3c800000, v17
	v_cos_f32_e32 v18, v17
	v_sin_f32_e64 v19, -v17
	v_add_u32_e32 v16, v16, v4
	s_waitcnt vmcnt(16)
	v_fmac_f32_e32 v15, v87, v18
	v_fmac_f32_e32 v20, v87, v19
	v_and_b32_e32 v17, 63, v16
	v_cvt_f32_ubyte0_e32 v17, v17
	v_mul_f32_e32 v17, 0x3c800000, v17
	v_cos_f32_e32 v18, v17
	v_sin_f32_e64 v19, -v17
	v_add_u32_e32 v16, v16, v4
	s_waitcnt vmcnt(15)
	v_fmac_f32_e32 v15, v88, v18
	v_fmac_f32_e32 v20, v88, v19
	v_and_b32_e32 v17, 63, v16
	v_cvt_f32_ubyte0_e32 v17, v17
	v_mul_f32_e32 v17, 0x3c800000, v17
	v_cos_f32_e32 v18, v17
	v_sin_f32_e64 v19, -v17
	v_add_u32_e32 v16, v16, v4
	s_waitcnt vmcnt(14)
	v_fmac_f32_e32 v15, v89, v18
	v_fmac_f32_e32 v20, v89, v19
	v_and_b32_e32 v17, 63, v16
	v_cvt_f32_ubyte0_e32 v17, v17
	v_mul_f32_e32 v17, 0x3c800000, v17
	v_cos_f32_e32 v18, v17
	v_sin_f32_e64 v19, -v17
	v_add_u32_e32 v16, v16, v4
	s_waitcnt vmcnt(13)
	v_fmac_f32_e32 v15, v90, v18
	v_fmac_f32_e32 v20, v90, v19
	v_and_b32_e32 v17, 63, v16
	v_cvt_f32_ubyte0_e32 v17, v17
	v_mul_f32_e32 v17, 0x3c800000, v17
	v_cos_f32_e32 v18, v17
	v_sin_f32_e64 v19, -v17
	v_add_u32_e32 v16, v16, v4
	s_waitcnt vmcnt(12)
	v_fmac_f32_e32 v15, v91, v18
	v_fmac_f32_e32 v20, v91, v19
	v_and_b32_e32 v17, 63, v16
	v_cvt_f32_ubyte0_e32 v17, v17
	v_mul_f32_e32 v17, 0x3c800000, v17
	v_cos_f32_e32 v18, v17
	v_sin_f32_e64 v19, -v17
	v_add_u32_e32 v16, v16, v4
	s_waitcnt vmcnt(11)
	v_fmac_f32_e32 v15, v92, v18
	v_fmac_f32_e32 v20, v92, v19
	v_and_b32_e32 v17, 63, v16
	v_cvt_f32_ubyte0_e32 v17, v17
	v_mul_f32_e32 v17, 0x3c800000, v17
	v_cos_f32_e32 v18, v17
	v_sin_f32_e64 v19, -v17
	v_add_u32_e32 v16, v16, v4
	s_waitcnt vmcnt(10)
	v_fmac_f32_e32 v15, v93, v18
	v_fmac_f32_e32 v20, v93, v19
	v_and_b32_e32 v17, 63, v16
	v_cvt_f32_ubyte0_e32 v17, v17
	v_mul_f32_e32 v17, 0x3c800000, v17
	v_cos_f32_e32 v18, v17
	v_sin_f32_e64 v19, -v17
	v_add_u32_e32 v16, v16, v4
	s_waitcnt vmcnt(9)
	v_fmac_f32_e32 v15, v94, v18
	v_fmac_f32_e32 v20, v94, v19
	v_and_b32_e32 v17, 63, v16
	v_cvt_f32_ubyte0_e32 v17, v17
	v_mul_f32_e32 v17, 0x3c800000, v17
	v_cos_f32_e32 v18, v17
	v_sin_f32_e64 v19, -v17
	v_add_u32_e32 v16, v16, v4
	s_waitcnt vmcnt(8)
	v_fmac_f32_e32 v15, v95, v18
	v_fmac_f32_e32 v20, v95, v19
	v_and_b32_e32 v17, 63, v16
	v_cvt_f32_ubyte0_e32 v17, v17
	v_mul_f32_e32 v17, 0x3c800000, v17
	v_cos_f32_e32 v18, v17
	v_sin_f32_e64 v19, -v17
	v_add_u32_e32 v16, v16, v4
	s_waitcnt vmcnt(7)
	v_fmac_f32_e32 v15, v96, v18
	v_fmac_f32_e32 v20, v96, v19
	v_and_b32_e32 v17, 63, v16
	v_cvt_f32_ubyte0_e32 v17, v17
	v_mul_f32_e32 v17, 0x3c800000, v17
	v_cos_f32_e32 v18, v17
	v_sin_f32_e64 v19, -v17
	v_add_u32_e32 v16, v16, v4
	s_waitcnt vmcnt(6)
	v_fmac_f32_e32 v15, v97, v18
	v_fmac_f32_e32 v20, v97, v19
	v_and_b32_e32 v17, 63, v16
	v_cvt_f32_ubyte0_e32 v17, v17
	v_mul_f32_e32 v17, 0x3c800000, v17
	v_cos_f32_e32 v18, v17
	v_sin_f32_e64 v19, -v17
	v_add_u32_e32 v16, v16, v4
	s_waitcnt vmcnt(5)
	v_fmac_f32_e32 v15, v98, v18
	v_fmac_f32_e32 v20, v98, v19
	v_and_b32_e32 v17, 63, v16
	v_cvt_f32_ubyte0_e32 v17, v17
	v_mul_f32_e32 v17, 0x3c800000, v17
	v_cos_f32_e32 v18, v17
	v_sin_f32_e64 v19, -v17
	v_add_u32_e32 v16, v16, v4
	s_waitcnt vmcnt(4)
	v_fmac_f32_e32 v15, v99, v18
	v_fmac_f32_e32 v20, v99, v19
	v_and_b32_e32 v17, 63, v16
	v_cvt_f32_ubyte0_e32 v17, v17
	v_mul_f32_e32 v17, 0x3c800000, v17
	v_cos_f32_e32 v18, v17
	v_sin_f32_e64 v19, -v17
	v_add_u32_e32 v16, v16, v4
	s_waitcnt vmcnt(3)
	v_fmac_f32_e32 v15, v100, v18
	v_fmac_f32_e32 v20, v100, v19
	v_and_b32_e32 v17, 63, v16
	v_cvt_f32_ubyte0_e32 v17, v17
	v_mul_f32_e32 v17, 0x3c800000, v17
	v_cos_f32_e32 v18, v17
	v_sin_f32_e64 v19, -v17
	v_add_u32_e32 v16, v16, v4
	s_waitcnt vmcnt(2)
	v_fmac_f32_e32 v15, v101, v18
	v_fmac_f32_e32 v20, v101, v19
	v_and_b32_e32 v17, 63, v16
	v_cvt_f32_ubyte0_e32 v17, v17
	v_mul_f32_e32 v17, 0x3c800000, v17
	v_cos_f32_e32 v18, v17
	v_sin_f32_e64 v19, -v17
	v_add_u32_e32 v16, v16, v4
	s_waitcnt vmcnt(1)
	v_fmac_f32_e32 v15, v102, v18
	v_fmac_f32_e32 v20, v102, v19
	v_and_b32_e32 v17, 63, v16
	v_cvt_f32_ubyte0_e32 v17, v17
	v_mul_f32_e32 v17, 0x3c800000, v17
	v_cos_f32_e32 v18, v17
	v_sin_f32_e64 v19, -v17
	v_add_u32_e32 v16, v16, v4
	s_waitcnt vmcnt(0)
	v_fmac_f32_e32 v15, v103, v18
	v_fmac_f32_e32 v20, v103, v19
	v_mul_f32_e32 v10, 0x3e000000, v15
	v_mul_f32_e32 v11, 0x3e000000, v20
	v_cvt_pk_bf16_f32 v10, v10, s0
	v_cvt_pk_bf16_f32 v11, v11, s0
	v_mul_u32_u24_e32 v12, 0x300, v8
	v_lshl_add_u32 v12, v5, 6, v12
	v_add_u32_e32 v12, v12, v4
	v_lshlrev_b32_e32 v188, 1, v12
	v_add_u32_e32 v3, s84, v3
	s_mov_b32 s0, 0x5ffff
	v_lshl_add_u64 v[6:7], s[8:9], 0, v[188:189]
	v_cmp_lt_i32_e32 vcc, s0, v3
	s_or_b64 s[54:55], vcc, s[54:55]
	v_subrev_u16_e32 v1, s84, v1
	global_store_short v[6:7], v10, off
	global_store_short v[6:7], v11, off offset:768
	s_andn2_b64 exec, exec, s[54:55]
	s_cbranch_execnz .LBB0_309

; DI float2 cmul(float2 x, float2 y) { return make_float2(x.x * y.x - x.y * y.y, x.x * y.y + x.y * y.x); }
; DI void phase_prep(const Params& P, int layer, int gtid, int nthr) {
;     ...
;     float* ktab = (float*)(ws + WS_KTAB);
;     for (int idx = gtid; idx < S5G * 2 * 4 * 256; idx += nthr) {
;         const int q = idx & 15, p = (idx >> 4) & 15, kb = (idx >> 8) & 3, d = (idx >> 10) & 1, g = idx >> 11;
;         const int ig = (layer * 2 + d) * S5G + g; float acc[8];
; #pragma unroll
;         for (int k = 0; k < 8; ++k) acc[k] = 0.f;
;         for (int n = 0; n < 64; ++n) {
;             const S5c c = s5_load(ldt, lre, lim, layer, d, g, n);
;             const float2 bb = cmul(s5_coef(c), make_float2(bre[((size_t)ig * 64 + n) * 16 + q], bim[((size_t)ig * 64 + n) * 16 + q]));
;             const float2 cc = make_float2(cre[((size_t)ig * 16 + p) * 64 + n], cim[((size_t)ig * 16 + p) * 64 + n]);
.LBB0_320:
	v_and_b32_e32 v4, 0x100, v0
	s_mov_b32 s0, 0x18000
	v_cmp_gt_u32_e64 s[8:9], s0, v0
	v_cmp_eq_u32_e32 vcc, 0, v4
	s_nop 1
	s_and_b64 vcc, vcc, s[8:9]
	s_and_saveexec_b64 s[6:7], vcc
	s_cbranch_execz .LBB0_325
	v_and_b32_e32 v4, 15, v2
	s_add_u32 s12, s44, 0x80000
	v_readlane_b32 s8, v254, 58
	v_readlane_b32 s0, v254, 17
	v_lshlrev_b32_e32 v188, 2, v4
	s_addc_u32 s13, s45, 0
	s_lshl_b32 s16, s8, 1
	v_and_b32_e32 v1, 0xff, v2
	v_lshl_add_u32 v3, v2, 2, s0
	v_readlane_b32 s0, v254, 18
	s_waitcnt lgkmcnt(0)
	v_lshl_add_u64 v[4:5], s[26:27], 0, v[188:189]
	v_lshl_add_u64 v[6:7], s[40:41], 0, v[188:189]
	s_mov_b64 s[14:15], 0
	v_lshrrev_b32_e32 v28, 9, v0
	v_and_b32_e32 v29, 0xff, v0
	v_lshl_or_b32 v28, v28, 8, v29
	v_readlane_b32 s9, v254, 59

; #define LAS __attribute__((address_space(3)))
; DI void attn_unit(LAS unsigned char* lds, const bf16_t* Q, const bf16_t* Kn, const bf16_t* Kpe, const bf16_t* Vt, bf16_t* O, int b, int h, int qb) {
;     ...
;     for (int kt = 0; kt < 64; ++kt) {
;         const int buf = kt & 1;
;         LAS unsigned char* kb = Ks + buf * KBUF; LAS unsigned char* vb = Vs + buf * VBUF;
;         f32x16 s[2][2];
; #pragma unroll
;         for (int j = 0; j < 2; ++j) { const float negm = -mrun[j];
; #pragma unroll
;             for (int i = 0; i < 16; ++i) { s[j][0][i] = negm; s[j][1][i] = negm; } }
;         if (wid < 4) __builtin_amdgcn_s_setprio(3); else __builtin_amdgcn_s_setprio(1);
; #pragma unroll
;         for (int t = 0; t < 6; ++t) {
;             const bf16x8 ka0 = *(const LAS bf16x8*)(kb + r32 * KPITCH + (16 * t + 8 * hi) * 2);
;             const bf16x8 ka1 = *(const LAS bf16x8*)(kb + (32 + r32) * KPITCH + (16 * t + 8 * hi) * 2);
; #pragma unroll
;             for (int j = 0; j < 2; ++j) {
;                 s[j][0] = __builtin_amdgcn_mfma_f32_32x32x16_bf16(ka0, qf[j][t], s[j][0], 0, 0, 0);
;                 s[j][1] = __builtin_amdgcn_mfma_f32_32x32x16_bf16(ka1, qf[j][t], s[j][1], 0, 0, 0);
;             }
;         }
;         __builtin_amdgcn_s_setprio(0);
;         __builtin_amdgcn_sched_barrier(0);
;         if (kt + 1 < 64) {
;             rk = *(const u32x4*)(kn_b + (kn_o + (unsigned)(kt + 1) * 4096u)); rv = *(const u32x4*)(vt_b + (vt_o + (unsigned)(kt + 1) * 64u));
;             if (tid < 256) rp = *(const u32x4*)(kp_b + (kp_o + (unsigned)(kt + 1) * 2048u));
;         }
.Lat_loop:
	s_cmp_lg_u32 s29, 0x1f000
	s_cselect_b64 s[16:17], -1, 0
	s_and_b64 vcc, exec, s[26:27]
	s_cbranch_vccnz .Lat_p1b
	s_andn2_b64 vcc, exec, s[16:17]
	s_cbranch_vccnz .Lat_p1a
	v_mov_b32_e32 v184, v216
	v_mov_b32_e32 v185, v189
	v_lshl_add_u64 v[180:181], v[188:189], 1, s[20:21]
	v_lshl_add_u64 v[184:185], v[184:185], 1, s[24:25]
	global_load_dwordx4 v[180:183], v[180:181], off
	s_nop 0
	global_load_dwordx4 v[184:187], v[184:185], off
	v_add_u32_e32 v176, s29, v243
	v_mov_b32_e32 v177, v189
	v_lshl_add_u64 v[176:177], v[176:177], 1, s[22:23]
	global_load_dwordx4 v[176:179], v[176:177], off
.Lat_p1a:
	s_setprio 3
	s_branch .Lat_h1

; #define LAS __attribute__((address_space(3)))
; DI void attn_unit(LAS unsigned char* lds, const bf16_t* Q, const bf16_t* Kn, const bf16_t* Kpe, const bf16_t* Vt, bf16_t* O, int b, int h, int qb) {
;     ...
;         f32x16 s[2][2];
; #pragma unroll
;         for (int j = 0; j < 2; ++j) { const float negm = -mrun[j];
; #pragma unroll
;             for (int i = 0; i < 16; ++i) { s[j][0][i] = negm; s[j][1][i] = negm; } }
;         if (wid < 4) __builtin_amdgcn_s_setprio(3); else __builtin_amdgcn_s_setprio(1);
; #pragma unroll
;         for (int t = 0; t < 6; ++t) {
;             const bf16x8 ka0 = *(const LAS bf16x8*)(kb + r32 * KPITCH + (16 * t + 8 * hi) * 2);
;             const bf16x8 ka1 = *(const LAS bf16x8*)(kb + (32 + r32) * KPITCH + (16 * t + 8 * hi) * 2);
; #pragma unroll
;             for (int j = 0; j < 2; ++j) {
;                 s[j][0] = __builtin_amdgcn_mfma_f32_32x32x16_bf16(ka0, qf[j][t], s[j][0], 0, 0, 0);
;                 s[j][1] = __builtin_amdgcn_mfma_f32_32x32x16_bf16(ka1, qf[j][t], s[j][1], 0, 0, 0);
;             }
;         }
;         __builtin_amdgcn_s_setprio(0);
;         __builtin_amdgcn_sched_barrier(0);
;         if (kt + 1 < 64) {
;             rk = *(const u32x4*)(kn_b + (kn_o + (unsigned)(kt + 1) * 4096u)); rv = *(const u32x4*)(vt_b + (vt_o + (unsigned)(kt + 1) * 64u));
;             if (tid < 256) rp = *(const u32x4*)(kp_b + (kp_o + (unsigned)(kt + 1) * 2048u));
;         }
;         __builtin_amdgcn_sched_barrier(0);
;         float mx[2];
; #pragma unroll
;         for (int j = 0; j < 2; ++j) {
;             mx[j] = fmaxf(s[j][0][0], s[j][1][0]);
; #pragma unroll
;             for (int i = 1; i < 16; ++i) mx[j] = fmaxf(mx[j], fmaxf(s[j][0][i], s[j][1][i]));
;         }
;         { const float o0 = __shfl_xor(mx[0], 32), o1 = __shfl_xor(mx[1], 32); mx[0] = fmaxf(mx[0], o0); mx[1] = fmaxf(mx[1], o1); }
;         if (kt == 0 || __builtin_amdgcn_ballot_w64(fmaxf(mx[0], mx[1]) > 6.0f) != 0ull) {
.Lat_h1:
	s_and_b32 s30, s28, 1
	s_mul_i32 s2, s30, 0x3400
	v_add_u32_e32 v217, s2, v239
	ds_read_b128 v[218:221], v217
	ds_read_b128 v[222:225], v217 offset:6656
	v_xor_b32_e32 v64, 0x80000000, v215
	v_xor_b32_e32 v80, 0x80000000, v214
	v_mov_b32_e32 v65, v64
	v_mov_b32_e32 v66, v64
	v_mov_b32_e32 v67, v64
	v_mov_b32_e32 v68, v64
	v_mov_b32_e32 v69, v64
	v_mov_b32_e32 v70, v64
	v_mov_b32_e32 v71, v64
	v_mov_b32_e32 v72, v64
	v_mov_b32_e32 v73, v64
	v_mov_b32_e32 v74, v64
	v_mov_b32_e32 v75, v64
	v_mov_b32_e32 v76, v64
	v_mov_b32_e32 v77, v64
	v_mov_b32_e32 v78, v64
	v_mov_b32_e32 v79, v64
	v_mov_b32_e32 v81, v80
	v_mov_b32_e32 v82, v80
	v_mov_b32_e32 v83, v80
	v_mov_b32_e32 v84, v80
	v_mov_b32_e32 v85, v80
	v_mov_b32_e32 v86, v80
	v_mov_b32_e32 v87, v80
	v_mov_b32_e32 v88, v80
	v_mov_b32_e32 v89, v80
	v_mov_b32_e32 v90, v80
	v_mov_b32_e32 v91, v80
	v_mov_b32_e32 v92, v80
	v_mov_b32_e32 v93, v80
	v_mov_b32_e32 v94, v80
	v_mov_b32_e32 v95, v80
	s_waitcnt lgkmcnt(1)
	v_mfma_f32_32x32x16_bf16 v[112:127], v[218:221], v[172:175], v[64:79]
	s_waitcnt lgkmcnt(0)
	v_mfma_f32_32x32x16_bf16 v[64:79], v[222:225], v[172:175], v[64:79]
	v_mfma_f32_32x32x16_bf16 v[96:111], v[218:221], v[148:151], v[80:95]
	ds_read_b128 v[218:221], v217 offset:32
	v_mfma_f32_32x32x16_bf16 v[80:95], v[222:225], v[148:151], v[80:95]
	ds_read_b128 v[222:225], v217 offset:6688
	s_waitcnt lgkmcnt(1)
	v_mfma_f32_32x32x16_bf16 v[112:127], v[218:221], v[128:131], v[112:127]
	s_waitcnt lgkmcnt(0)
	v_mfma_f32_32x32x16_bf16 v[64:79], v[222:225], v[128:131], v[64:79]
	v_mfma_f32_32x32x16_bf16 v[96:111], v[218:221], v[152:155], v[96:111]
	ds_read_b128 v[218:221], v217 offset:64
	v_mfma_f32_32x32x16_bf16 v[80:95], v[222:225], v[152:155], v[80:95]
	ds_read_b128 v[222:225], v217 offset:6720
	s_waitcnt lgkmcnt(1)
	v_mfma_f32_32x32x16_bf16 v[112:127], v[218:221], v[132:135], v[112:127]
	s_waitcnt lgkmcnt(0)
	v_mfma_f32_32x32x16_bf16 v[64:79], v[222:225], v[132:135], v[64:79]
	v_mfma_f32_32x32x16_bf16 v[96:111], v[218:221], v[156:159], v[96:111]
	ds_read_b128 v[218:221], v217 offset:96
	v_mfma_f32_32x32x16_bf16 v[80:95], v[222:225], v[156:159], v[80:95]
	ds_read_b128 v[222:225], v217 offset:6752
	s_waitcnt lgkmcnt(1)
	v_mfma_f32_32x32x16_bf16 v[112:127], v[218:221], v[136:139], v[112:127]
	s_waitcnt lgkmcnt(0)
	v_mfma_f32_32x32x16_bf16 v[64:79], v[222:225], v[136:139], v[64:79]
	v_mfma_f32_32x32x16_bf16 v[96:111], v[218:221], v[160:163], v[96:111]
	ds_read_b128 v[218:221], v217 offset:128
	v_mfma_f32_32x32x16_bf16 v[80:95], v[222:225], v[160:163], v[80:95]
	ds_read_b128 v[222:225], v217 offset:6784
	s_waitcnt lgkmcnt(1)
	v_mfma_f32_32x32x16_bf16 v[112:127], v[218:221], v[140:143], v[112:127]
	s_waitcnt lgkmcnt(0)
	v_mfma_f32_32x32x16_bf16 v[64:79], v[222:225], v[140:143], v[64:79]
	v_mfma_f32_32x32x16_bf16 v[96:111], v[218:221], v[164:167], v[96:111]
	ds_read_b128 v[218:221], v217 offset:160
	v_mfma_f32_32x32x16_bf16 v[80:95], v[222:225], v[164:167], v[80:95]
	ds_read_b128 v[222:225], v217 offset:6816
	s_waitcnt lgkmcnt(1)
	v_mfma_f32_32x32x16_bf16 v[112:127], v[218:221], v[144:147], v[112:127]
	s_waitcnt lgkmcnt(0)
	v_mfma_f32_32x32x16_bf16 v[64:79], v[222:225], v[144:147], v[64:79]
	v_mfma_f32_32x32x16_bf16 v[96:111], v[218:221], v[168:171], v[96:111]
	v_mfma_f32_32x32x16_bf16 v[80:95], v[222:225], v[168:171], v[80:95]
	s_setprio 0
	s_andn2_b64 vcc, exec, s[16:17]
	s_cbranch_vccnz .Lat_hmax
	s_and_b64 vcc, exec, s[26:27]
	s_cbranch_vccz .Lat_hmax
	s_xor_b32 s2, s30, 1
	s_mul_i32 s6, s2, 0x3400
	v_add_u32_e32 v217, s6, v210
	s_waitcnt vmcnt(1)
	ds_write_b128 v217, v[180:183]
	s_mulk_i32 s2, 0x2200
	v_add_u32_e32 v217, s2, v211
	v_add_u32_e32 v217, 0x6800, v217
	s_waitcnt vmcnt(0)
	ds_write2_b64 v217, v[184:185], v[186:187] offset1:1
.Lat_hmax:
	s_nop 3
	v_max3_f32 v217, v112, v113, v114
	v_max3_f32 v218, v120, v121, v122
	v_max3_f32 v217, v217, v115, v116
	v_max3_f32 v218, v218, v123, v124
	v_max3_f32 v217, v217, v117, v118
	v_max3_f32 v218, v218, v125, v126
	v_max3_f32 v219, v64, v65, v66
	v_max3_f32 v220, v72, v73, v74
	v_max3_f32 v219, v219, v67, v68
	v_max3_f32 v220, v220, v75, v76
	v_max3_f32 v219, v219, v69, v70
	v_max3_f32 v220, v220, v77, v78
	v_max3_f32 v217, v217, v218, v119
	v_max3_f32 v219, v219, v220, v127
	v_max3_f32 v217, v217, v219, v71
	v_max_f32_e32 v217, v79, v217
	v_max3_f32 v218, v96, v97, v98
	v_max3_f32 v219, v104, v105, v106
	v_max3_f32 v218, v218, v99, v100
	v_max3_f32 v219, v219, v107, v108
	v_max3_f32 v218, v218, v101, v102
	v_max3_f32 v219, v219, v109, v110
	v_max3_f32 v220, v80, v81, v82
	v_max3_f32 v221, v88, v89, v90
	v_max3_f32 v220, v220, v83, v84
	v_max3_f32 v221, v221, v91, v92
	v_max3_f32 v220, v220, v85, v86
	v_max3_f32 v221, v221, v93, v94
	v_max3_f32 v218, v218, v219, v103
	v_max3_f32 v220, v220, v221, v111
	v_max3_f32 v218, v218, v220, v87
	v_max_f32_e32 v219, v95, v218
	s_nop 1
	v_permlane32_swap_b32_e32 v217, v219
	v_max_f32_e32 v218, v217, v219
	v_mov_b32_e32 v217, v218
	s_nop 1
	v_permlane32_swap_b32_e32 v218, v217
	v_max_f32_e32 v219, v218, v217
.Lat_mid:
	s_waitcnt lgkmcnt(0)
	s_barrier
	s_and_b64 vcc, exec, s[26:27]
	s_cbranch_vccz .Lat_max
	s_cmp_lt_i32 s29, 0x1e800
	s_cbranch_scc0 .Lat_max
	v_add_u32_e32 v180, 0x1000, v188
	v_mov_b32_e32 v181, v189
	v_mov_b32_e32 v184, v216
	v_mov_b32_e32 v185, v189
	v_lshl_add_u64 v[180:181], v[180:181], 1, s[20:21]
	v_lshl_add_u64 v[184:185], v[184:185], 1, s[24:25]
	global_load_dwordx4 v[180:183], v[180:181], off
	s_nop 0
	global_load_dwordx4 v[184:187], v[184:185], off offset:128
.Lat_max:
	s_mov_b32 s2, 0x40c00000
	v_cmp_lt_f32_e32 vcc, s2, v219
	s_cmp_eq_u32 s28, 0
	s_cbranch_scc1 .Lat_resc
	s_cbranch_vccz .Lat_noresc
